# v40 + the third counted vmcnt wait of the peeled first gate/up K iteration dropped too (its operands were prefetched and drained before the previous epilogue's stores)
# speedup vs baseline: 1.0017x; 1.0017x over previous
.LBB0_145:
	s_ashr_i32 s17, s16, 31
	s_lshl_b64 s[18:19], s[16:17], 19
	s_add_u32 s18, s36, s18
	s_addc_u32 s19, s37, s19
	s_and_b64 s[20:21], s[2:3], exec
	s_cselect_b32 s17, s19, s25
	s_cselect_b32 s50, s18, s24
	s_ashr_i32 s15, s14, 31
	s_lshl_b64 s[20:21], s[14:15], 19
	s_add_u32 s20, s34, s20
	s_addc_u32 s21, s35, s21
	s_and_b64 s[28:29], s[2:3], exec
	s_cselect_b32 s15, s21, s27
	s_cselect_b32 s51, s20, s26
	s_add_u32 s24, s24, 0x40080
	s_addc_u32 s25, s25, 0
	s_add_u32 s52, s26, 0x100
	s_addc_u32 s53, s27, 0
	s_mov_b32 s54, -2
	s_add_u32 s26, s24, 0xfffc0080
	s_addc_u32 s27, s25, -1
	s_add_i32 s55, 0, 0x10000
	s_cmp_eq_u32 s54, 12
	s_cselect_b32 s29, s17, s27
	s_cselect_b32 s28, s50, s26
	v_add_u32_e32 v140, s55, v143
	s_cselect_b32 s27, s15, s53
	s_cselect_b32 s26, s51, s52
	s_add_i32 s60, 0, 0x14000
	ds_read_b128 v[150:153], v140
	ds_read_b128 v[154:157], v140 offset:1024
	ds_read_b128 v[158:161], v140 offset:2048
	ds_read_b128 v[162:165], v140 offset:3072
	v_add_u32_e32 v140, s60, v143
	ds_read_b128 v[166:169], v140
	ds_read_b128 v[170:173], v140 offset:1024
	ds_read_b128 v[174:177], v140 offset:2048
	ds_read_b128 v[178:181], v140 offset:3072
	v_lshl_add_u64 v[140:141], s[24:25], 0, v[136:137]
	s_add_i32 m0, s40, 0xc000
	ds_read_b128 v[182:185], v148
	ds_read_b128 v[186:189], v148 offset:1024
	ds_read_b128 v[190:193], v148 offset:2048
	ds_read_b128 v[202:205], v148 offset:3072
	ds_read_b128 v[206:209], v148 offset:4096
	ds_read_b128 v[210:213], v148 offset:5120
	ds_read_b128 v[214:217], v148 offset:6144
	ds_read_b128 v[218:221], v148 offset:7168
	global_load_lds_dwordx4 v[140:141], off
	v_lshl_add_u64 v[140:141], s[24:25], 0, v[138:139]
	s_add_i32 m0, s40, 0xe000
	s_nop 0
	global_load_lds_dwordx4 v[140:141], off
	s_waitcnt lgkmcnt(0)
	s_barrier
	s_setprio 1
	s_waitcnt lgkmcnt(0)
	v_mfma_f32_16x16x32_bf16 v[126:129], v[150:153], v[182:185], 0
	v_mfma_f32_16x16x32_bf16 v[118:121], v[158:161], v[182:185], 0
	v_mfma_f32_16x16x32_bf16 v[110:113], v[150:153], v[190:193], 0
	v_mfma_f32_16x16x32_bf16 v[102:105], v[158:161], v[190:193], 0
	v_mfma_f32_16x16x32_bf16 v[92:95], v[150:153], v[206:209], 0
	v_mfma_f32_16x16x32_bf16 v[84:87], v[158:161], v[206:209], 0
	v_mfma_f32_16x16x32_bf16 v[76:79], v[150:153], v[214:217], 0
	v_mfma_f32_16x16x32_bf16 v[68:71], v[158:161], v[214:217], 0
	v_mfma_f32_16x16x32_bf16 v[126:129], v[154:157], v[186:189], v[126:129]
	v_mfma_f32_16x16x32_bf16 v[118:121], v[162:165], v[186:189], v[118:121]
	v_mfma_f32_16x16x32_bf16 v[110:113], v[154:157], v[202:205], v[110:113]
	v_mfma_f32_16x16x32_bf16 v[102:105], v[162:165], v[202:205], v[102:105]
	v_mfma_f32_16x16x32_bf16 v[92:95], v[154:157], v[210:213], v[92:95]
	v_mfma_f32_16x16x32_bf16 v[84:87], v[162:165], v[210:213], v[84:87]
	v_mfma_f32_16x16x32_bf16 v[76:79], v[154:157], v[218:221], v[76:79]
	v_mfma_f32_16x16x32_bf16 v[68:71], v[162:165], v[218:221], v[68:71]
	s_setprio 0
	s_setprio 1
	v_mfma_f32_16x16x32_bf16 v[122:125], v[166:169], v[182:185], 0
	v_mfma_f32_16x16x32_bf16 v[114:117], v[174:177], v[182:185], 0
	v_mfma_f32_16x16x32_bf16 v[106:109], v[166:169], v[190:193], 0
	v_mfma_f32_16x16x32_bf16 v[98:101], v[174:177], v[190:193], 0
	v_mfma_f32_16x16x32_bf16 v[88:91], v[166:169], v[206:209], 0
	v_mfma_f32_16x16x32_bf16 v[80:83], v[174:177], v[206:209], 0
	v_mfma_f32_16x16x32_bf16 v[72:75], v[166:169], v[214:217], 0
	v_mfma_f32_16x16x32_bf16 v[64:67], v[174:177], v[214:217], 0
	v_mfma_f32_16x16x32_bf16 v[122:125], v[170:173], v[186:189], v[122:125]
	v_mfma_f32_16x16x32_bf16 v[114:117], v[178:181], v[186:189], v[114:117]
	v_mfma_f32_16x16x32_bf16 v[106:109], v[170:173], v[202:205], v[106:109]
	v_mfma_f32_16x16x32_bf16 v[98:101], v[178:181], v[202:205], v[98:101]
	v_mfma_f32_16x16x32_bf16 v[88:91], v[170:173], v[210:213], v[88:91]
	v_mfma_f32_16x16x32_bf16 v[80:83], v[178:181], v[210:213], v[80:83]
	v_mfma_f32_16x16x32_bf16 v[72:75], v[170:173], v[218:221], v[72:75]
	v_mfma_f32_16x16x32_bf16 v[64:67], v[178:181], v[218:221], v[64:67]
	s_setprio 0
	s_barrier
	s_add_i32 s55, s55, s39
	v_lshl_add_u64 v[140:141], s[26:27], 0, v[96:97]
	s_mov_b32 m0, s55
	ds_read_b128 v[182:185], v148 offset:16384
	ds_read_b128 v[186:189], v148 offset:17408
	ds_read_b128 v[190:193], v148 offset:18432
	ds_read_b128 v[202:205], v148 offset:19456
	ds_read_b128 v[206:209], v148 offset:20480
	ds_read_b128 v[210:213], v148 offset:21504
	ds_read_b128 v[214:217], v148 offset:22528
	ds_read_b128 v[218:221], v148 offset:23552
	global_load_lds_dwordx4 v[140:141], off
	s_add_i32 m0, s55, 0x2000
	s_add_u32 s56, s26, 0x40000
	v_lshl_add_u64 v[194:195], s[26:27], 0, v[130:131]
	s_addc_u32 s57, s27, 0
	s_add_i32 s55, s60, s39
	global_load_lds_dwordx4 v[194:195], off
	v_lshl_add_u64 v[196:197], s[56:57], 0, v[96:97]
	s_mov_b32 m0, s55
	v_lshl_add_u64 v[198:199], s[28:29], 0, v[132:133]
	global_load_lds_dwordx4 v[196:197], off
	v_lshl_add_u64 v[196:197], s[56:57], 0, v[130:131]
	s_add_i32 m0, s55, 0x2000
	s_nop 0
	global_load_lds_dwordx4 v[196:197], off
	v_lshl_add_u64 v[196:197], s[28:29], 0, v[134:135]
	s_mov_b32 m0, s40
	s_nop 0
	global_load_lds_dwordx4 v[196:197], off
	s_mov_b32 m0, s41
	s_nop 0
	global_load_lds_dwordx4 v[198:199], off
	s_waitcnt lgkmcnt(0)
	s_barrier
	s_setprio 1
	s_waitcnt lgkmcnt(0)
	v_mfma_f32_16x16x32_bf16 v[60:63], v[150:153], v[182:185], 0
	v_mfma_f32_16x16x32_bf16 v[52:55], v[158:161], v[182:185], 0
	v_mfma_f32_16x16x32_bf16 v[44:47], v[150:153], v[190:193], 0
	v_mfma_f32_16x16x32_bf16 v[36:39], v[158:161], v[190:193], 0
	v_mfma_f32_16x16x32_bf16 v[28:31], v[150:153], v[206:209], 0
	v_mfma_f32_16x16x32_bf16 v[20:23], v[158:161], v[206:209], 0
	v_mfma_f32_16x16x32_bf16 v[12:15], v[150:153], v[214:217], 0
	v_mfma_f32_16x16x32_bf16 v[4:7], v[158:161], v[214:217], 0
	v_mfma_f32_16x16x32_bf16 v[60:63], v[154:157], v[186:189], v[60:63]
	v_mfma_f32_16x16x32_bf16 v[52:55], v[162:165], v[186:189], v[52:55]
	v_mfma_f32_16x16x32_bf16 v[44:47], v[154:157], v[202:205], v[44:47]
	v_mfma_f32_16x16x32_bf16 v[36:39], v[162:165], v[202:205], v[36:39]
	v_mfma_f32_16x16x32_bf16 v[28:31], v[154:157], v[210:213], v[28:31]
	v_mfma_f32_16x16x32_bf16 v[20:23], v[162:165], v[210:213], v[20:23]
	v_mfma_f32_16x16x32_bf16 v[12:15], v[154:157], v[218:221], v[12:15]
	v_mfma_f32_16x16x32_bf16 v[4:7], v[162:165], v[218:221], v[4:7]
	s_setprio 0
	s_setprio 1
	v_mfma_f32_16x16x32_bf16 v[56:59], v[166:169], v[182:185], 0
	v_mfma_f32_16x16x32_bf16 v[48:51], v[174:177], v[182:185], 0
	v_mfma_f32_16x16x32_bf16 v[40:43], v[166:169], v[190:193], 0
	v_mfma_f32_16x16x32_bf16 v[32:35], v[174:177], v[190:193], 0
	v_mfma_f32_16x16x32_bf16 v[24:27], v[166:169], v[206:209], 0
	v_mfma_f32_16x16x32_bf16 v[16:19], v[174:177], v[206:209], 0
	v_mfma_f32_16x16x32_bf16 v[8:11], v[166:169], v[214:217], 0
	v_mfma_f32_16x16x32_bf16 v[0:3], v[174:177], v[214:217], 0
	v_mfma_f32_16x16x32_bf16 v[56:59], v[170:173], v[186:189], v[56:59]
	v_mfma_f32_16x16x32_bf16 v[48:51], v[178:181], v[186:189], v[48:51]
	v_mfma_f32_16x16x32_bf16 v[40:43], v[170:173], v[202:205], v[40:43]
	v_mfma_f32_16x16x32_bf16 v[32:35], v[178:181], v[202:205], v[32:35]
	v_mfma_f32_16x16x32_bf16 v[24:27], v[170:173], v[210:213], v[24:27]
	v_mfma_f32_16x16x32_bf16 v[16:19], v[178:181], v[210:213], v[16:19]
	v_mfma_f32_16x16x32_bf16 v[8:11], v[170:173], v[218:221], v[8:11]
	v_mfma_f32_16x16x32_bf16 v[0:3], v[178:181], v[218:221], v[0:3]
	s_setprio 0
	s_barrier
	s_add_i32 s55, 0, 0x18000
	v_add_u32_e32 v149, s55, v143
	s_add_i32 s56, 0, 0x1c000
	ds_read_b128 v[150:153], v149
	ds_read_b128 v[154:157], v149 offset:1024
	ds_read_b128 v[158:161], v149 offset:2048
	ds_read_b128 v[162:165], v149 offset:3072
	v_add_u32_e32 v149, s56, v143
	ds_read_b128 v[166:169], v149
	ds_read_b128 v[170:173], v149 offset:1024
	ds_read_b128 v[174:177], v149 offset:2048
	ds_read_b128 v[178:181], v149 offset:3072
	s_add_u32 s28, s28, 0x40000
	s_addc_u32 s29, s29, 0
	s_mov_b32 m0, s42
	v_lshl_add_u64 v[200:201], s[28:29], 0, v[134:135]
	ds_read_b128 v[182:185], v148 offset:32768
	ds_read_b128 v[186:189], v148 offset:33792
	ds_read_b128 v[190:193], v148 offset:34816
	ds_read_b128 v[202:205], v148 offset:35840
	ds_read_b128 v[206:209], v148 offset:36864
	ds_read_b128 v[210:213], v148 offset:37888
	ds_read_b128 v[214:217], v148 offset:38912
	ds_read_b128 v[218:221], v148 offset:39936
	global_load_lds_dwordx4 v[200:201], off
	v_lshl_add_u64 v[200:201], s[28:29], 0, v[132:133]
	s_mov_b32 m0, s43
	s_nop 0
	global_load_lds_dwordx4 v[200:201], off
	s_waitcnt lgkmcnt(0)
	s_barrier
	s_setprio 1
	s_waitcnt lgkmcnt(0)
	v_mfma_f32_16x16x32_bf16 v[126:129], v[150:153], v[182:185], v[126:129]
	v_mfma_f32_16x16x32_bf16 v[118:121], v[158:161], v[182:185], v[118:121]
	v_mfma_f32_16x16x32_bf16 v[110:113], v[150:153], v[190:193], v[110:113]
	v_mfma_f32_16x16x32_bf16 v[102:105], v[158:161], v[190:193], v[102:105]
	v_mfma_f32_16x16x32_bf16 v[92:95], v[150:153], v[206:209], v[92:95]
	v_mfma_f32_16x16x32_bf16 v[84:87], v[158:161], v[206:209], v[84:87]
	v_mfma_f32_16x16x32_bf16 v[76:79], v[150:153], v[214:217], v[76:79]
	v_mfma_f32_16x16x32_bf16 v[68:71], v[158:161], v[214:217], v[68:71]
	v_mfma_f32_16x16x32_bf16 v[126:129], v[154:157], v[186:189], v[126:129]
	v_mfma_f32_16x16x32_bf16 v[118:121], v[162:165], v[186:189], v[118:121]
	v_mfma_f32_16x16x32_bf16 v[110:113], v[154:157], v[202:205], v[110:113]
	v_mfma_f32_16x16x32_bf16 v[102:105], v[162:165], v[202:205], v[102:105]
	v_mfma_f32_16x16x32_bf16 v[92:95], v[154:157], v[210:213], v[92:95]
	v_mfma_f32_16x16x32_bf16 v[84:87], v[162:165], v[210:213], v[84:87]
	v_mfma_f32_16x16x32_bf16 v[76:79], v[154:157], v[218:221], v[76:79]
	v_mfma_f32_16x16x32_bf16 v[68:71], v[162:165], v[218:221], v[68:71]
	s_setprio 0
	s_setprio 1
	v_mfma_f32_16x16x32_bf16 v[122:125], v[166:169], v[182:185], v[122:125]
	v_mfma_f32_16x16x32_bf16 v[114:117], v[174:177], v[182:185], v[114:117]
	v_mfma_f32_16x16x32_bf16 v[106:109], v[166:169], v[190:193], v[106:109]
	v_mfma_f32_16x16x32_bf16 v[98:101], v[174:177], v[190:193], v[98:101]
	v_mfma_f32_16x16x32_bf16 v[88:91], v[166:169], v[206:209], v[88:91]
	v_mfma_f32_16x16x32_bf16 v[80:83], v[174:177], v[206:209], v[80:83]
	v_mfma_f32_16x16x32_bf16 v[72:75], v[166:169], v[214:217], v[72:75]
	v_mfma_f32_16x16x32_bf16 v[64:67], v[174:177], v[214:217], v[64:67]
	v_mfma_f32_16x16x32_bf16 v[122:125], v[170:173], v[186:189], v[122:125]
	v_mfma_f32_16x16x32_bf16 v[114:117], v[178:181], v[186:189], v[114:117]
	v_mfma_f32_16x16x32_bf16 v[106:109], v[170:173], v[202:205], v[106:109]
	v_mfma_f32_16x16x32_bf16 v[98:101], v[178:181], v[202:205], v[98:101]
	v_mfma_f32_16x16x32_bf16 v[88:91], v[170:173], v[210:213], v[88:91]
	v_mfma_f32_16x16x32_bf16 v[80:83], v[178:181], v[210:213], v[80:83]
	v_mfma_f32_16x16x32_bf16 v[72:75], v[170:173], v[218:221], v[72:75]
	v_mfma_f32_16x16x32_bf16 v[64:67], v[178:181], v[218:221], v[64:67]
	s_setprio 0
	s_barrier
	s_add_i32 s28, s55, s39
	v_lshl_add_u64 v[140:141], v[140:141], 0, s[64:65]
	s_mov_b32 m0, s28
	ds_read_b128 v[182:185], v148 offset:49152
	ds_read_b128 v[186:189], v148 offset:50176
	ds_read_b128 v[190:193], v148 offset:51200
	ds_read_b128 v[202:205], v148 offset:52224
	ds_read_b128 v[206:209], v148 offset:53248
	ds_read_b128 v[210:213], v148 offset:54272
	ds_read_b128 v[214:217], v148 offset:55296
	ds_read_b128 v[218:221], v148 offset:56320
	global_load_lds_dwordx4 v[140:141], off
	s_add_i32 m0, s28, 0x2000
	s_add_u32 s26, s26, 0x40080
	v_lshl_add_u64 v[140:141], v[194:195], 0, s[64:65]
	s_addc_u32 s27, s27, 0
	s_add_i32 s28, s56, s39
	global_load_lds_dwordx4 v[140:141], off
	v_lshl_add_u64 v[140:141], s[26:27], 0, v[96:97]
	s_mov_b32 m0, s28
	s_nop 0
	global_load_lds_dwordx4 v[140:141], off
	v_lshl_add_u64 v[140:141], s[26:27], 0, v[130:131]
	s_add_i32 m0, s28, 0x2000
	s_nop 0
	global_load_lds_dwordx4 v[140:141], off
	v_lshl_add_u64 v[140:141], v[196:197], 0, s[64:65]
	s_mov_b32 m0, s44
	s_nop 0
	global_load_lds_dwordx4 v[140:141], off
	v_lshl_add_u64 v[140:141], v[198:199], 0, s[64:65]
	s_mov_b32 m0, s45
	s_nop 0
	global_load_lds_dwordx4 v[140:141], off
	s_waitcnt vmcnt(8)
	s_waitcnt lgkmcnt(0)
	s_barrier
	s_setprio 1
	s_waitcnt lgkmcnt(0)
	v_mfma_f32_16x16x32_bf16 v[60:63], v[150:153], v[182:185], v[60:63]
	v_mfma_f32_16x16x32_bf16 v[52:55], v[158:161], v[182:185], v[52:55]
	v_mfma_f32_16x16x32_bf16 v[44:47], v[150:153], v[190:193], v[44:47]
	v_mfma_f32_16x16x32_bf16 v[36:39], v[158:161], v[190:193], v[36:39]
	v_mfma_f32_16x16x32_bf16 v[28:31], v[150:153], v[206:209], v[28:31]
	v_mfma_f32_16x16x32_bf16 v[20:23], v[158:161], v[206:209], v[20:23]
	v_mfma_f32_16x16x32_bf16 v[12:15], v[150:153], v[214:217], v[12:15]
	v_mfma_f32_16x16x32_bf16 v[4:7], v[158:161], v[214:217], v[4:7]
	v_mfma_f32_16x16x32_bf16 v[60:63], v[154:157], v[186:189], v[60:63]
	v_mfma_f32_16x16x32_bf16 v[52:55], v[162:165], v[186:189], v[52:55]
	v_mfma_f32_16x16x32_bf16 v[44:47], v[154:157], v[202:205], v[44:47]
	v_mfma_f32_16x16x32_bf16 v[36:39], v[162:165], v[202:205], v[36:39]
	v_mfma_f32_16x16x32_bf16 v[28:31], v[154:157], v[210:213], v[28:31]
	v_mfma_f32_16x16x32_bf16 v[20:23], v[162:165], v[210:213], v[20:23]
	v_mfma_f32_16x16x32_bf16 v[12:15], v[154:157], v[218:221], v[12:15]
	v_mfma_f32_16x16x32_bf16 v[4:7], v[162:165], v[218:221], v[4:7]
	s_setprio 0
	s_setprio 1
	v_mfma_f32_16x16x32_bf16 v[56:59], v[166:169], v[182:185], v[56:59]
	v_mfma_f32_16x16x32_bf16 v[48:51], v[174:177], v[182:185], v[48:51]
	v_mfma_f32_16x16x32_bf16 v[40:43], v[166:169], v[190:193], v[40:43]
	v_mfma_f32_16x16x32_bf16 v[32:35], v[174:177], v[190:193], v[32:35]
	v_mfma_f32_16x16x32_bf16 v[24:27], v[166:169], v[206:209], v[24:27]
	v_mfma_f32_16x16x32_bf16 v[16:19], v[174:177], v[206:209], v[16:19]
	v_mfma_f32_16x16x32_bf16 v[8:11], v[166:169], v[214:217], v[8:11]
	v_mfma_f32_16x16x32_bf16 v[0:3], v[174:177], v[214:217], v[0:3]
	v_mfma_f32_16x16x32_bf16 v[56:59], v[170:173], v[186:189], v[56:59]
	v_mfma_f32_16x16x32_bf16 v[48:51], v[178:181], v[186:189], v[48:51]
	v_mfma_f32_16x16x32_bf16 v[40:43], v[170:173], v[202:205], v[40:43]
	v_mfma_f32_16x16x32_bf16 v[32:35], v[178:181], v[202:205], v[32:35]
	v_mfma_f32_16x16x32_bf16 v[24:27], v[170:173], v[210:213], v[24:27]
	v_mfma_f32_16x16x32_bf16 v[16:19], v[178:181], v[210:213], v[16:19]
	v_mfma_f32_16x16x32_bf16 v[8:11], v[170:173], v[218:221], v[8:11]
	v_mfma_f32_16x16x32_bf16 v[0:3], v[178:181], v[218:221], v[0:3]
	s_setprio 0
	s_barrier
	s_add_i32 s54, s54, 2
	s_add_u32 s24, s24, 0x100
	s_addc_u32 s25, s25, 0
	s_add_u32 s52, s52, 0x100
	s_addc_u32 s53, s53, 0
	s_cmp_gt_u32 s54, 13
	s_cbranch_scc1 .Lgu_kdone
